# GEMM unit header: 127 v_mov accumulator zeroing -> 63 v_pk_mov_b32
# speedup vs baseline: 1.0049x; 1.0049x over previous
; template <class Epi, class Sched>
; __device__ __forceinline__ void gemm_phase(LAS unsigned char* lds, const Gemm g, const Sched& S, const Epi& E, const int tid) {
;     ...
;         for (int t = 0; t < nt; t += 2) {
;     ...
;         for (int a = 0; a < 2; ++a)
; #pragma unroll
;             for (int b = 0; b < 2; ++b)
; #pragma unroll
;                 for (int m = 0; m < 4; ++m)
; #pragma unroll
;                     for (int n = 0; n < 2; ++n) acc[a][b][m][n] = (f32x4){0.f, 0.f, 0.f, 0.f};
;         cur = nxt; cA = nA; cB = nB; ++ui;
.LBB0_243:
	s_add_u32 s28, s12, 0x100
	s_addc_u32 s29, s13, 0
	s_add_u32 s10, s14, 0x80
	v_mov_b32_e32 v0, 0
	s_addc_u32 s11, s15, 0
	s_mov_b32 s12, 0
	v_mov_b32_e32 v1, 0
	v_pk_mov_b32 v[2:3], v[0:1], v[0:1]
	v_pk_mov_b32 v[4:5], v[0:1], v[0:1]
	v_pk_mov_b32 v[6:7], v[0:1], v[0:1]
	v_pk_mov_b32 v[8:9], v[0:1], v[0:1]
	v_pk_mov_b32 v[10:11], v[0:1], v[0:1]
	v_pk_mov_b32 v[12:13], v[0:1], v[0:1]
	v_pk_mov_b32 v[14:15], v[0:1], v[0:1]
	v_pk_mov_b32 v[16:17], v[0:1], v[0:1]
	v_pk_mov_b32 v[18:19], v[0:1], v[0:1]
	v_pk_mov_b32 v[20:21], v[0:1], v[0:1]
	v_pk_mov_b32 v[22:23], v[0:1], v[0:1]
	v_pk_mov_b32 v[24:25], v[0:1], v[0:1]
	v_pk_mov_b32 v[26:27], v[0:1], v[0:1]
	v_pk_mov_b32 v[28:29], v[0:1], v[0:1]
	v_pk_mov_b32 v[30:31], v[0:1], v[0:1]
	v_pk_mov_b32 v[32:33], v[0:1], v[0:1]
	v_pk_mov_b32 v[34:35], v[0:1], v[0:1]
	v_pk_mov_b32 v[36:37], v[0:1], v[0:1]
	v_pk_mov_b32 v[38:39], v[0:1], v[0:1]
	v_pk_mov_b32 v[40:41], v[0:1], v[0:1]
	v_pk_mov_b32 v[42:43], v[0:1], v[0:1]
	v_pk_mov_b32 v[44:45], v[0:1], v[0:1]
	v_pk_mov_b32 v[46:47], v[0:1], v[0:1]
	v_pk_mov_b32 v[48:49], v[0:1], v[0:1]
	v_pk_mov_b32 v[50:51], v[0:1], v[0:1]
	v_pk_mov_b32 v[52:53], v[0:1], v[0:1]
	v_pk_mov_b32 v[54:55], v[0:1], v[0:1]
	v_pk_mov_b32 v[56:57], v[0:1], v[0:1]
	v_pk_mov_b32 v[58:59], v[0:1], v[0:1]
	v_pk_mov_b32 v[60:61], v[0:1], v[0:1]
	v_pk_mov_b32 v[62:63], v[0:1], v[0:1]
	v_pk_mov_b32 v[64:65], v[0:1], v[0:1]
	v_pk_mov_b32 v[66:67], v[0:1], v[0:1]
	v_pk_mov_b32 v[68:69], v[0:1], v[0:1]
	v_pk_mov_b32 v[70:71], v[0:1], v[0:1]
	v_pk_mov_b32 v[72:73], v[0:1], v[0:1]
	v_pk_mov_b32 v[74:75], v[0:1], v[0:1]
	v_pk_mov_b32 v[76:77], v[0:1], v[0:1]
	v_pk_mov_b32 v[78:79], v[0:1], v[0:1]
	v_pk_mov_b32 v[80:81], v[0:1], v[0:1]
	v_pk_mov_b32 v[82:83], v[0:1], v[0:1]
	v_pk_mov_b32 v[84:85], v[0:1], v[0:1]
	v_pk_mov_b32 v[86:87], v[0:1], v[0:1]
	v_pk_mov_b32 v[88:89], v[0:1], v[0:1]
	v_pk_mov_b32 v[90:91], v[0:1], v[0:1]
	v_pk_mov_b32 v[92:93], v[0:1], v[0:1]
	v_pk_mov_b32 v[94:95], v[0:1], v[0:1]
	v_pk_mov_b32 v[96:97], v[0:1], v[0:1]
	v_pk_mov_b32 v[98:99], v[0:1], v[0:1]
	v_pk_mov_b32 v[100:101], v[0:1], v[0:1]
	v_pk_mov_b32 v[102:103], v[0:1], v[0:1]
	v_pk_mov_b32 v[104:105], v[0:1], v[0:1]
	v_pk_mov_b32 v[106:107], v[0:1], v[0:1]
	v_pk_mov_b32 v[108:109], v[0:1], v[0:1]
	v_pk_mov_b32 v[110:111], v[0:1], v[0:1]
	v_pk_mov_b32 v[112:113], v[0:1], v[0:1]
	v_pk_mov_b32 v[114:115], v[0:1], v[0:1]
	v_pk_mov_b32 v[116:117], v[0:1], v[0:1]
	v_pk_mov_b32 v[118:119], v[0:1], v[0:1]
	v_pk_mov_b32 v[120:121], v[0:1], v[0:1]
	v_pk_mov_b32 v[122:123], v[0:1], v[0:1]
	v_pk_mov_b32 v[124:125], v[0:1], v[0:1]
	v_pk_mov_b32 v[126:127], v[0:1], v[0:1]
